# attention: per-subtile active-flag inversion done with s_not_b64 instead of v_cndmask+v_cmp_ne ballot
# speedup vs baseline: 1.0070x; 1.0070x over previous
; #define LAS __attribute__((address_space(3)))
; __device__ __forceinline__ void attn_phase(LAS unsigned char* lds, const bf16_t* qkv, bf16_t* og, float* lse, int G, int bid) {
;     ...
;             f32x4 sc[16];
; #pragma unroll
;             for (int s = 0; s < 16; ++s) {
;                 sc[s] = (f32x4){0.f, 0.f, 0.f, 0.f};
;                 if (s >= wid && s <= wid + 8 && (s >= 8 || blk > 0)) {
;                     LAS unsigned char* kb = (s < 8 ? Kp : Kc) + (16 * (s & 7) + fr) * KP + 16 * fq;
; #pragma unroll
;                     for (int kk = 0; kk < 4; ++kk) {
;                         const bf16x8 kf = *(const LAS bf16x8*)(kb + 64 * kk);
;                         sc[s] = __builtin_amdgcn_mfma_f32_16x16x32_bf16(kf, Q[kk], sc[s], 0, 0, 0);
;                     }
;                 }
;             }
.LBB0_1124:
	s_and_b32 s81, s79, 1
	s_lshl_b32 s1, s81, 7
	s_add_i32 s0, s77, s78
	s_xor_b32 s82, s1, 0x80
	s_cmp_lg_u32 s0, 0
	s_cselect_b64 s[30:31], -1, 0
	s_and_b64 s[0:1], s[62:63], s[30:31]
	s_mul_i32 s80, s82, 0x110
	v_mov_b32_e32 v52, 0
	s_not_b64 s[38:39], s[0:1]
	s_andn2_b64 vcc, exec, s[0:1]
	v_add_u32_e32 v0, s80, v154
	v_mov_b32_e32 v60, 0
	v_mov_b32_e32 v61, 0
	v_mov_b32_e32 v62, 0
	v_mov_b32_e32 v63, 0
	s_cbranch_vccnz .LBB0_1126
	ds_read_b128 v[226:229], v0
	ds_read_b128 v[230:233], v0 offset:64
	ds_read_b128 v[234:237], v0 offset:128
	ds_read_b128 v[238:241], v0 offset:192
	s_waitcnt lgkmcnt(3)
	v_mfma_f32_16x16x32_bf16 v[54:57], v[226:229], v[128:131], 0
	s_waitcnt lgkmcnt(2)
	v_mfma_f32_16x16x32_bf16 v[54:57], v[230:233], v[124:127], v[54:57]
	s_waitcnt lgkmcnt(1)
	v_mfma_f32_16x16x32_bf16 v[54:57], v[234:237], v[120:123], v[54:57]
	s_waitcnt lgkmcnt(0)
	v_mfma_f32_16x16x32_bf16 v[60:63], v[238:241], v[116:119], v[54:57]
.LBB0_1126:
	s_and_b64 s[0:1], s[4:5], s[30:31]
	s_not_b64 s[36:37], s[0:1]
	s_andn2_b64 vcc, exec, s[0:1]
	v_mov_b32_e32 v53, 0
	v_mov_b32_e32 v54, 0
	v_mov_b32_e32 v55, 0
	s_cbranch_vccnz .LBB0_1128
	ds_read_b128 v[226:229], v0 offset:4352
	ds_read_b128 v[230:233], v0 offset:4416
	ds_read_b128 v[234:237], v0 offset:4480
	ds_read_b128 v[238:241], v0 offset:4544
	s_waitcnt lgkmcnt(3)
	v_mfma_f32_16x16x32_bf16 v[52:55], v[226:229], v[128:131], 0
	s_waitcnt lgkmcnt(2)
	v_mfma_f32_16x16x32_bf16 v[52:55], v[230:233], v[124:127], v[52:55]
	s_waitcnt lgkmcnt(1)
	v_mfma_f32_16x16x32_bf16 v[52:55], v[234:237], v[120:123], v[52:55]
	s_waitcnt lgkmcnt(0)
	v_mfma_f32_16x16x32_bf16 v[52:55], v[238:241], v[116:119], v[52:55]
.LBB0_1128:
	s_and_b64 s[0:1], s[6:7], s[30:31]
	v_mov_b32_e32 v56, 0
	s_not_b64 s[40:41], s[0:1]
	s_andn2_b64 vcc, exec, s[0:1]
	v_mov_b32_e32 v72, 0
	v_mov_b32_e32 v73, 0
	v_mov_b32_e32 v74, 0
	v_mov_b32_e32 v75, 0
	s_cbranch_vccnz .LBB0_1130
	ds_read_b128 v[226:229], v0 offset:8704
	ds_read_b128 v[230:233], v0 offset:8768
	ds_read_b128 v[234:237], v0 offset:8832
	ds_read_b128 v[238:241], v0 offset:8896
	s_waitcnt lgkmcnt(3)
	v_mfma_f32_16x16x32_bf16 v[64:67], v[226:229], v[128:131], 0
	s_waitcnt lgkmcnt(2)
	v_mfma_f32_16x16x32_bf16 v[64:67], v[230:233], v[124:127], v[64:67]
	s_waitcnt lgkmcnt(1)
	v_mfma_f32_16x16x32_bf16 v[64:67], v[234:237], v[120:123], v[64:67]
	s_waitcnt lgkmcnt(0)
	v_mfma_f32_16x16x32_bf16 v[72:75], v[238:241], v[116:119], v[64:67]
.LBB0_1130:
	s_and_b64 s[0:1], s[8:9], s[30:31]
	s_not_b64 s[34:35], s[0:1]
	s_andn2_b64 vcc, exec, s[0:1]
	v_mov_b32_e32 v57, 0
	v_mov_b32_e32 v58, 0
	v_mov_b32_e32 v59, 0
	s_cbranch_vccnz .LBB0_1132
	ds_read_b128 v[226:229], v0 offset:13056
	ds_read_b128 v[230:233], v0 offset:13120
	ds_read_b128 v[234:237], v0 offset:13184
	ds_read_b128 v[238:241], v0 offset:13248
	s_waitcnt lgkmcnt(3)
	v_mfma_f32_16x16x32_bf16 v[56:59], v[226:229], v[128:131], 0
	s_waitcnt lgkmcnt(2)
	v_mfma_f32_16x16x32_bf16 v[56:59], v[230:233], v[124:127], v[56:59]
	s_waitcnt lgkmcnt(1)
	v_mfma_f32_16x16x32_bf16 v[56:59], v[234:237], v[120:123], v[56:59]
	s_waitcnt lgkmcnt(0)
	v_mfma_f32_16x16x32_bf16 v[56:59], v[238:241], v[116:119], v[56:59]
.LBB0_1132:
	s_and_b64 s[0:1], s[10:11], s[30:31]
	v_mov_b32_e32 v64, 0
	s_not_b64 s[42:43], s[0:1]
	s_andn2_b64 vcc, exec, s[0:1]
	v_mov_b32_e32 v80, 0
	v_mov_b32_e32 v81, 0
	v_mov_b32_e32 v82, 0
	v_mov_b32_e32 v83, 0
	s_cbranch_vccnz .LBB0_1134
	ds_read_b128 v[226:229], v0 offset:17408
	ds_read_b128 v[230:233], v0 offset:17472
	ds_read_b128 v[234:237], v0 offset:17536
	ds_read_b128 v[238:241], v0 offset:17600
	s_waitcnt lgkmcnt(3)
	v_mfma_f32_16x16x32_bf16 v[66:69], v[226:229], v[128:131], 0
	s_waitcnt lgkmcnt(2)
	v_mfma_f32_16x16x32_bf16 v[66:69], v[230:233], v[124:127], v[66:69]
	s_waitcnt lgkmcnt(1)
	v_mfma_f32_16x16x32_bf16 v[66:69], v[234:237], v[120:123], v[66:69]
	s_waitcnt lgkmcnt(0)
	v_mfma_f32_16x16x32_bf16 v[80:83], v[238:241], v[116:119], v[66:69]
.LBB0_1134:
	s_and_b64 s[44:45], s[12:13], s[30:31]
	s_not_b64 s[0:1], s[44:45]
	s_andn2_b64 vcc, exec, s[44:45]
	v_mov_b32_e32 v65, 0
	v_mov_b32_e32 v66, 0
	v_mov_b32_e32 v67, 0
	s_cbranch_vccnz .LBB0_1136
	ds_read_b128 v[226:229], v0 offset:21760
	ds_read_b128 v[230:233], v0 offset:21824
	ds_read_b128 v[234:237], v0 offset:21888
	ds_read_b128 v[238:241], v0 offset:21952
	s_waitcnt lgkmcnt(3)
	v_mfma_f32_16x16x32_bf16 v[64:67], v[226:229], v[128:131], 0
	s_waitcnt lgkmcnt(2)
	v_mfma_f32_16x16x32_bf16 v[64:67], v[230:233], v[124:127], v[64:67]
	s_waitcnt lgkmcnt(1)
	v_mfma_f32_16x16x32_bf16 v[64:67], v[234:237], v[120:123], v[64:67]
	s_waitcnt lgkmcnt(0)
	v_mfma_f32_16x16x32_bf16 v[64:67], v[238:241], v[116:119], v[64:67]
.LBB0_1136:
	s_and_b64 s[46:47], s[14:15], s[30:31]
	v_mov_b32_e32 v68, 0
	s_not_b64 s[44:45], s[46:47]
	s_andn2_b64 vcc, exec, s[46:47]
	v_mov_b32_e32 v88, 0
	v_mov_b32_e32 v89, 0
	v_mov_b32_e32 v90, 0
	v_mov_b32_e32 v91, 0
	s_cbranch_vccnz .LBB0_1138
	ds_read_b128 v[226:229], v0 offset:26112
	ds_read_b128 v[230:233], v0 offset:26176
	ds_read_b128 v[234:237], v0 offset:26240
	ds_read_b128 v[238:241], v0 offset:26304
	s_waitcnt lgkmcnt(3)
	v_mfma_f32_16x16x32_bf16 v[76:79], v[226:229], v[128:131], 0
	s_waitcnt lgkmcnt(2)
	v_mfma_f32_16x16x32_bf16 v[76:79], v[230:233], v[124:127], v[76:79]
	s_waitcnt lgkmcnt(1)
	v_mfma_f32_16x16x32_bf16 v[76:79], v[234:237], v[120:123], v[76:79]
	s_waitcnt lgkmcnt(0)
	v_mfma_f32_16x16x32_bf16 v[88:91], v[238:241], v[116:119], v[76:79]
; #define LAS __attribute__((address_space(3)))
; __device__ __forceinline__ void attn_phase(LAS unsigned char* lds, const bf16_t* qkv, bf16_t* og, float* lse, int G, int bid) {
;     ...
;             f32x4 sc[16];
; #pragma unroll
;             for (int s = 0; s < 16; ++s) {
;                 sc[s] = (f32x4){0.f, 0.f, 0.f, 0.f};
;                 if (s >= wid && s <= wid + 8 && (s >= 8 || blk > 0)) {
;                     LAS unsigned char* kb = (s < 8 ? Kp : Kc) + (16 * (s & 7) + fr) * KP + 16 * fq;
; #pragma unroll
;                     for (int kk = 0; kk < 4; ++kk) {
;                         const bf16x8 kf = *(const LAS bf16x8*)(kb + 64 * kk);
;                         sc[s] = __builtin_amdgcn_mfma_f32_16x16x32_bf16(kf, Q[kk], sc[s], 0, 0, 0);
;                     }
;                 }
;             }
;             float mx = -3.0e38f;
.LBB0_1138:
	s_and_b64 s[46:47], s[64:65], s[30:31]
	s_not_b64 s[30:31], s[46:47]
	s_andn2_b64 vcc, exec, s[46:47]
	v_mov_b32_e32 v69, 0
	v_mov_b32_e32 v70, 0
	v_mov_b32_e32 v71, 0
	s_cbranch_vccnz .LBB0_1140
	ds_read_b128 v[226:229], v0 offset:30464
	ds_read_b128 v[230:233], v0 offset:30528
	ds_read_b128 v[234:237], v0 offset:30592
	ds_read_b128 v[238:241], v0 offset:30656
	s_waitcnt lgkmcnt(3)
	v_mfma_f32_16x16x32_bf16 v[68:71], v[226:229], v[128:131], 0
	s_waitcnt lgkmcnt(2)
	v_mfma_f32_16x16x32_bf16 v[68:71], v[230:233], v[124:127], v[68:71]
	s_waitcnt lgkmcnt(1)
	v_mfma_f32_16x16x32_bf16 v[68:71], v[234:237], v[120:123], v[68:71]
	s_waitcnt lgkmcnt(0)
	v_mfma_f32_16x16x32_bf16 v[68:71], v[238:241], v[116:119], v[68:71]
.LBB0_1140:
	s_mul_i32 s81, s81, 0x8800
	v_mov_b32_e32 v76, 0
	s_not_b64 s[46:47], s[66:67]
	s_andn2_b64 vcc, exec, s[66:67]
	v_add_u32_e32 v0, s81, v154
	v_mov_b32_e32 v96, 0
	v_mov_b32_e32 v97, 0
	v_mov_b32_e32 v98, 0
	v_mov_b32_e32 v99, 0
	s_cbranch_vccnz .LBB0_1142
	ds_read_b128 v[226:229], v0
	ds_read_b128 v[230:233], v0 offset:64
	ds_read_b128 v[234:237], v0 offset:128
	ds_read_b128 v[238:241], v0 offset:192
	s_waitcnt lgkmcnt(3)
	v_mfma_f32_16x16x32_bf16 v[84:87], v[226:229], v[128:131], 0
	s_waitcnt lgkmcnt(2)
	v_mfma_f32_16x16x32_bf16 v[84:87], v[230:233], v[124:127], v[84:87]
	s_waitcnt lgkmcnt(1)
	v_mfma_f32_16x16x32_bf16 v[84:87], v[234:237], v[120:123], v[84:87]
	s_waitcnt lgkmcnt(0)
	v_mfma_f32_16x16x32_bf16 v[96:99], v[238:241], v[116:119], v[84:87]
.LBB0_1142:
	s_not_b64 s[48:49], s[16:17]
	s_andn2_b64 vcc, exec, s[16:17]
	v_mov_b32_e32 v77, 0
	v_mov_b32_e32 v78, 0
	v_mov_b32_e32 v79, 0
	s_cbranch_vccnz .LBB0_1144
	ds_read_b128 v[226:229], v0 offset:4352
	ds_read_b128 v[230:233], v0 offset:4416
	ds_read_b128 v[234:237], v0 offset:4480
	ds_read_b128 v[238:241], v0 offset:4544
	s_waitcnt lgkmcnt(3)
	v_mfma_f32_16x16x32_bf16 v[76:79], v[226:229], v[128:131], 0
	s_waitcnt lgkmcnt(2)
	v_mfma_f32_16x16x32_bf16 v[76:79], v[230:233], v[124:127], v[76:79]
	s_waitcnt lgkmcnt(1)
	v_mfma_f32_16x16x32_bf16 v[76:79], v[234:237], v[120:123], v[76:79]
	s_waitcnt lgkmcnt(0)
	v_mfma_f32_16x16x32_bf16 v[76:79], v[238:241], v[116:119], v[76:79]
.LBB0_1144:
	v_mov_b32_e32 v84, 0
	s_not_b64 s[50:51], s[18:19]
	s_andn2_b64 vcc, exec, s[18:19]
	v_mov_b32_e32 v104, 0
	v_mov_b32_e32 v105, 0
	v_mov_b32_e32 v106, 0
	v_mov_b32_e32 v107, 0
	s_cbranch_vccnz .LBB0_1146
	ds_read_b128 v[226:229], v0 offset:8704
	ds_read_b128 v[230:233], v0 offset:8768
	ds_read_b128 v[234:237], v0 offset:8832
	ds_read_b128 v[238:241], v0 offset:8896
	s_waitcnt lgkmcnt(3)
	v_mfma_f32_16x16x32_bf16 v[92:95], v[226:229], v[128:131], 0
	s_waitcnt lgkmcnt(2)
	v_mfma_f32_16x16x32_bf16 v[92:95], v[230:233], v[124:127], v[92:95]
	s_waitcnt lgkmcnt(1)
	v_mfma_f32_16x16x32_bf16 v[92:95], v[234:237], v[120:123], v[92:95]
	s_waitcnt lgkmcnt(0)
	v_mfma_f32_16x16x32_bf16 v[104:107], v[238:241], v[116:119], v[92:95]
.LBB0_1146:
	s_not_b64 s[52:53], s[20:21]
	s_andn2_b64 vcc, exec, s[20:21]
	v_mov_b32_e32 v85, 0
	v_mov_b32_e32 v86, 0
	v_mov_b32_e32 v87, 0
	s_cbranch_vccnz .LBB0_1148
	ds_read_b128 v[226:229], v0 offset:13056
	ds_read_b128 v[230:233], v0 offset:13120
	ds_read_b128 v[234:237], v0 offset:13184
	ds_read_b128 v[238:241], v0 offset:13248
	s_waitcnt lgkmcnt(3)
	v_mfma_f32_16x16x32_bf16 v[84:87], v[226:229], v[128:131], 0
	s_waitcnt lgkmcnt(2)
	v_mfma_f32_16x16x32_bf16 v[84:87], v[230:233], v[124:127], v[84:87]
	s_waitcnt lgkmcnt(1)
	v_mfma_f32_16x16x32_bf16 v[84:87], v[234:237], v[120:123], v[84:87]
	s_waitcnt lgkmcnt(0)
	v_mfma_f32_16x16x32_bf16 v[84:87], v[238:241], v[116:119], v[84:87]
.LBB0_1148:
	v_mov_b32_e32 v92, 0
	s_not_b64 s[54:55], s[22:23]
	s_andn2_b64 vcc, exec, s[22:23]
	v_mov_b32_e32 v108, 0
	v_mov_b32_e32 v109, 0
	v_mov_b32_e32 v110, 0
	v_mov_b32_e32 v111, 0
	s_cbranch_vccnz .LBB0_1150
	ds_read_b128 v[226:229], v0 offset:17408
	ds_read_b128 v[230:233], v0 offset:17472
	ds_read_b128 v[234:237], v0 offset:17536
	ds_read_b128 v[238:241], v0 offset:17600
	s_waitcnt lgkmcnt(3)
	v_mfma_f32_16x16x32_bf16 v[100:103], v[226:229], v[128:131], 0
	s_waitcnt lgkmcnt(2)
	v_mfma_f32_16x16x32_bf16 v[100:103], v[230:233], v[124:127], v[100:103]
	s_waitcnt lgkmcnt(1)
	v_mfma_f32_16x16x32_bf16 v[100:103], v[234:237], v[120:123], v[100:103]
	s_waitcnt lgkmcnt(0)
	v_mfma_f32_16x16x32_bf16 v[108:111], v[238:241], v[116:119], v[100:103]
.LBB0_1150:
	s_not_b64 s[56:57], s[24:25]
	s_andn2_b64 vcc, exec, s[24:25]
	v_mov_b32_e32 v93, 0
	v_mov_b32_e32 v94, 0
	v_mov_b32_e32 v95, 0
	s_cbranch_vccnz .LBB0_1152
	ds_read_b128 v[226:229], v0 offset:21760
	ds_read_b128 v[230:233], v0 offset:21824
	ds_read_b128 v[234:237], v0 offset:21888
	ds_read_b128 v[238:241], v0 offset:21952
	s_waitcnt lgkmcnt(3)
	v_mfma_f32_16x16x32_bf16 v[92:95], v[226:229], v[128:131], 0
	s_waitcnt lgkmcnt(2)
	v_mfma_f32_16x16x32_bf16 v[92:95], v[230:233], v[124:127], v[92:95]
	s_waitcnt lgkmcnt(1)
	v_mfma_f32_16x16x32_bf16 v[92:95], v[234:237], v[120:123], v[92:95]
	s_waitcnt lgkmcnt(0)
	v_mfma_f32_16x16x32_bf16 v[92:95], v[238:241], v[116:119], v[92:95]
.LBB0_1152:
	v_mov_b32_e32 v100, 0
	s_not_b64 s[58:59], s[26:27]
	s_andn2_b64 vcc, exec, s[26:27]
	v_mov_b32_e32 v112, 0
	v_mov_b32_e32 v113, 0
	v_mov_b32_e32 v114, 0
	v_mov_b32_e32 v115, 0
	s_cbranch_vccnz .LBB0_1154
	ds_read_b128 v[226:229], v0 offset:26112
	ds_read_b128 v[230:233], v0 offset:26176
	ds_read_b128 v[234:237], v0 offset:26240
	ds_read_b128 v[238:241], v0 offset:26304
	s_waitcnt lgkmcnt(3)
	v_mfma_f32_16x16x32_bf16 v[112:115], v[226:229], v[128:131], 0
	s_waitcnt lgkmcnt(2)
	v_mfma_f32_16x16x32_bf16 v[112:115], v[230:233], v[124:127], v[112:115]
	s_waitcnt lgkmcnt(1)
	v_mfma_f32_16x16x32_bf16 v[112:115], v[234:237], v[120:123], v[112:115]
	s_waitcnt lgkmcnt(0)
	v_mfma_f32_16x16x32_bf16 v[112:115], v[238:241], v[116:119], v[112:115]
.LBB0_1154:
	s_not_b64 s[60:61], s[28:29]
	s_andn2_b64 vcc, exec, s[28:29]
	v_mov_b32_e32 v101, 0
	v_mov_b32_e32 v102, 0
	v_mov_b32_e32 v103, 0
	s_cbranch_vccz .LBB0_1190
	s_and_b64 vcc, exec, s[38:39]
	v_mov_b32_e32 v0, 0xff61b1e6
	s_cbranch_vccz .LBB0_1191
